# C->D seam uses an XCD-local barrier (no L2 writeback, poll own XCC flag) guarded by a placement check word
# speedup vs baseline: 1.0109x; 1.0035x over previous
.LBB0_8:
	s_or_b64 exec, exec, s[4:5]
	s_waitcnt lgkmcnt(0)
	s_add_u32 s2, s86, 0x1000
	s_addc_u32 s3, s87, 0
	v_writelane_b32 v250, s2, 4
	s_barrier
	s_nop 0
	v_writelane_b32 v250, s3, 5
	s_getreg_b32 s2, hwreg(HW_REG_XCC_ID, 0, 4)
	s_and_b32 s2, s2, 15
	v_writelane_b32 v250, s2, 6
	v_cmp_eq_u32_e32 vcc, 0, v0
	s_and_saveexec_b64 s[2:3], vcc
	s_cbranch_execz .LBB0_11
	s_mov_b64 s[4:5], exec
	v_mbcnt_lo_u32_b32 v1, s4, 0
	v_mbcnt_hi_u32_b32 v1, s5, v1
	v_cmp_eq_u32_e32 vcc, 0, v1
	s_and_b64 s[6:7], exec, vcc
	s_mov_b64 exec, s[6:7]
	s_cbranch_execz .LBB0_11
	v_readlane_b32 s6, v250, 6
	s_bcnt1_i32_b64 s4, s[4:5]
	s_lshl_b32 s6, s6, 8
	v_mov_b32_e32 v2, s4
	v_readlane_b32 s4, v250, 4
	v_mov_b32_e32 v1, s6
	v_readlane_b32 s5, v250, 5
	s_nop 4
	global_atomic_add v1, v2, s[4:5] offset:1024
	v_readlane_b32 s6, v250, 6
	v_readlane_b32 s7, v250, 2
	s_and_b32 s7, s7, 7
	s_cmp_eq_u32 s6, s7
	s_cbranch_scc1 .Lxb_place_ok
	v_mov_b32_e32 v1, 0x3400
	s_nop 0
	global_atomic_add v1, v2, s[4:5]
.Lxb_place_ok:
.LBB0_11:
	s_or_b64 exec, exec, s[2:3]
	s_load_dwordx2 s[4:5], s[0:1], 0xd8
	s_lshr_b32 s76, s73, 6
	v_and_b32_e32 v227, 63, v0
	s_mov_b32 s55, 1
	s_waitcnt lgkmcnt(0)
	s_cmp_lt_i32 s4, 1
	s_cselect_b64 s[2:3], -1, 0
	v_writelane_b32 v250, s4, 8
	s_cmp_gt_i32 s5, 0
	s_nop 0
	v_writelane_b32 v250, s5, 9
	s_cselect_b64 s[4:5], -1, 0
	s_and_b64 s[2:3], s[2:3], s[4:5]
	v_writelane_b32 v250, s2, 10
	s_andn2_b64 vcc, exec, s[2:3]
	s_nop 0
	v_writelane_b32 v250, s3, 11
	s_cbranch_vccnz .LBB0_68
	s_cmp_lt_i32 s55, 1
	s_cbranch_scc1 .LBB0_68
	v_writelane_b32 v250, s73, 12
	s_cmpk_eq_i32 s33, 0x100
	s_movk_i32 s2, 0x900
	v_readlane_b32 s3, v250, 3
	s_cselect_b32 s54, s2, 0x3b00
	s_lshl_b32 s2, s3, 3
	s_add_i32 s2, s2, s76
	s_cmp_lt_i32 s2, s54
	v_writelane_b32 v250, s2, 13
	s_cselect_b64 s[40:41], -1, 0
	s_lshl_b32 s2, s76, 14
	s_add_i32 s2, s2, 0
	s_lshl_b32 s56, s33, 3
	s_load_dwordx4 s[28:31], s[0:1], 0x28
	s_load_dwordx4 s[36:39], s[0:1], 0x48
	s_add_u32 s57, s86, 0xc00000
	s_addc_u32 s52, s87, 0
	s_add_u32 s53, s86, 0x100000
	s_addc_u32 s60, s87, 0
	s_waitcnt lgkmcnt(0)
	s_add_u32 s42, s28, 0x1000
	s_addc_u32 s43, s29, 0
	s_add_u32 s44, s30, 0x1000
	s_addc_u32 s45, s31, 0
	s_add_u32 s50, s30, 0x2000
	s_addc_u32 s51, s31, 0
	s_add_u32 s58, s30, 0x3000
	s_addc_u32 s59, s31, 0
	s_add_u32 s4, s30, 0x4000
	v_writelane_b32 v250, s2, 14
	s_addc_u32 s5, s31, 0
	v_writelane_b32 v250, s4, 15
	s_mul_i32 s2, s33, s76
	v_mov_b32_e32 v31, 0
	v_writelane_b32 v250, s5, 16
	s_add_u32 s4, s30, 0x5000
	s_addc_u32 s5, s31, 0
	v_writelane_b32 v250, s4, 31
	s_mov_b32 s61, 0
	s_movk_i32 s62, 0x2000
	v_writelane_b32 v250, s5, 32
	s_add_u32 s4, s30, 0x6000
	s_addc_u32 s5, s31, 0
	v_writelane_b32 v250, s4, 33
	s_movk_i32 s63, 0x4000
	s_movk_i32 s64, 0x6000
	v_writelane_b32 v250, s5, 34
	s_add_u32 s4, s30, 0x7000
	s_addc_u32 s5, s31, 0
	v_writelane_b32 v250, s4, 35
	s_mov_b32 s65, 0x8000
	s_mov_b32 s66, 0xa000
	v_writelane_b32 v250, s5, 36
	s_add_u32 s4, s30, 0x8000
	s_addc_u32 s5, s31, 0
	v_writelane_b32 v250, s4, 37
	s_mov_b32 s67, 0xc000
	s_mov_b32 s68, 0xe000
	v_writelane_b32 v250, s5, 38
	s_add_u32 s4, s30, 0x9000
	s_addc_u32 s5, s31, 0
	v_writelane_b32 v250, s4, 39
	s_mov_b32 s69, 0x10000
	s_mov_b32 s70, 0x12000
	v_writelane_b32 v250, s5, 40
	s_add_u32 s4, s30, 0xa000
	s_addc_u32 s5, s31, 0
	v_writelane_b32 v250, s4, 41
	s_mov_b32 s71, 0x14000
	s_mov_b32 s72, 0x16000
	v_writelane_b32 v250, s5, 42
	s_add_u32 s4, s30, 0xb000
	s_addc_u32 s5, s31, 0
	v_writelane_b32 v250, s4, 43
	s_mov_b32 s73, 0x18000
	s_mov_b32 s74, 0x1a000
	v_writelane_b32 v250, s5, 44
	s_add_u32 s4, s30, 0xc000
	s_addc_u32 s5, s31, 0
	v_writelane_b32 v250, s4, 45
	s_mov_b32 s75, 0x1c000
	s_mov_b32 s77, 0x20000
	v_writelane_b32 v250, s5, 46
	s_add_u32 s4, s30, 0xd000
	s_addc_u32 s5, s31, 0
	v_writelane_b32 v250, s4, 47
	s_mov_b32 s78, 0x22000
	s_mov_b32 s79, 0x24000
	v_writelane_b32 v250, s5, 48
	s_add_u32 s4, s30, 0xe000
	s_addc_u32 s5, s31, 0
	v_writelane_b32 v250, s4, 49
	s_mov_b32 s80, 0x26000
	s_mov_b32 s81, 0x28000
	v_writelane_b32 v250, s5, 50
	s_add_u32 s4, s30, 0xf000
	s_addc_u32 s5, s31, 0
	v_writelane_b32 v250, s4, 51
	s_mov_b32 s82, 0x2a000
	s_mov_b32 s83, 0x2c000
	v_writelane_b32 v250, s5, 52
	s_add_u32 s4, s30, 0x10000
	s_addc_u32 s5, s31, 0
	v_writelane_b32 v250, s4, 53
	s_mov_b32 s88, 0x2e000
	s_mov_b32 s89, 0x30000
	v_writelane_b32 v250, s5, 54
	s_add_u32 s4, s30, 0x11000
	s_addc_u32 s5, s31, 0
	v_writelane_b32 v250, s4, 55
	s_mov_b32 s90, 0x32000
	s_mov_b32 s91, 0x34000
	v_writelane_b32 v250, s5, 56
	s_add_u32 s4, s30, 0x12000
	s_addc_u32 s5, s31, 0
	v_writelane_b32 v250, s4, 57
	s_mov_b32 s92, 0x36000
	s_mov_b32 s93, 0x38000
	v_writelane_b32 v250, s5, 58
	s_add_u32 s4, s30, 0x13000
	s_addc_u32 s5, s31, 0
	v_writelane_b32 v250, s4, 59
	s_mov_b32 s94, 0x3a000
	s_mov_b32 s95, 0x3c000
	v_writelane_b32 v250, s5, 60
	s_add_u32 s4, s30, 0x14000
	s_addc_u32 s5, s31, 0
	v_writelane_b32 v250, s4, 61
	s_mov_b32 s96, 0x3e000
	s_movk_i32 s97, 0x7fff
	v_writelane_b32 v250, s5, 62
	s_add_u32 s4, s30, 0x15000
	s_addc_u32 s5, s31, 0
	v_writelane_b32 v250, s4, 63
	s_movk_i32 s34, 0x4800
	s_nop 0
	v_writelane_b32 v251, s5, 0
	s_add_u32 s4, s30, 0x16000
	s_addc_u32 s5, s31, 0
	v_writelane_b32 v251, s4, 1
	s_nop 1
	v_writelane_b32 v251, s5, 2
	s_add_u32 s4, s30, 0x17000
	s_addc_u32 s5, s31, 0
	v_writelane_b32 v251, s4, 3
	s_nop 1
	v_writelane_b32 v251, s5, 4
	s_add_u32 s4, s30, 0x18000
	s_addc_u32 s5, s31, 0
	v_writelane_b32 v251, s4, 5
	s_nop 1
	v_writelane_b32 v251, s5, 6
	s_add_u32 s4, s30, 0x19000
	s_addc_u32 s5, s31, 0
	v_writelane_b32 v251, s4, 7
	s_nop 1
	v_writelane_b32 v251, s5, 8
	s_add_u32 s4, s30, 0x1a000
	s_addc_u32 s5, s31, 0
	v_writelane_b32 v251, s4, 9
	s_nop 1
	v_writelane_b32 v251, s5, 10
	s_add_u32 s4, s30, 0x1b000
	s_addc_u32 s5, s31, 0
	v_writelane_b32 v251, s4, 11
	s_nop 1
	v_writelane_b32 v251, s5, 12
	s_add_u32 s4, s30, 0x1c000
	s_addc_u32 s5, s31, 0
	v_writelane_b32 v251, s4, 13
	s_nop 1
	v_writelane_b32 v251, s5, 14
	s_add_u32 s4, s30, 0x1d000
	s_addc_u32 s5, s31, 0
	v_writelane_b32 v251, s4, 15
	s_nop 1
	v_writelane_b32 v251, s5, 16
	s_add_u32 s4, s30, 0x1e000
	s_addc_u32 s5, s31, 0
	v_writelane_b32 v251, s4, 17
	s_nop 1
	v_writelane_b32 v251, s5, 18
	s_add_u32 s4, s30, 0x1f000
	s_addc_u32 s5, s31, 0
	v_writelane_b32 v251, s4, 19
	s_add_i32 s2, s3, s2
	s_cmpk_lt_i32 s2, 0x300
	v_writelane_b32 v251, s5, 20
	v_writelane_b32 v251, s76, 21
	v_writelane_b32 v251, s2, 22
	s_cselect_b64 s[2:3], -1, 0
	v_writelane_b32 v251, s2, 24
	s_cmp_lg_u64 s[38:39], 0
	s_cselect_b64 s[46:47], -1, 0
	v_writelane_b32 v251, s3, 25
	s_add_u32 s2, s36, 0x56a000
	s_addc_u32 s3, s37, 0
	s_load_dwordx2 s[36:37], s[0:1], 0x58
	s_load_dwordx8 s[20:27], s[0:1], 0x90
	v_writelane_b32 v251, s2, 26
	s_mov_b32 s76, 0x1e000
	s_nop 0
	v_writelane_b32 v251, s3, 27
	v_writelane_b32 v251, s58, 28
	s_mov_b32 s2, 0xffff0000
	s_movk_i32 s3, 0x5800
	v_writelane_b32 v251, s59, 29
	s_branch .LBB0_16

.LBB0_1345:
	v_readlane_b32 s0, v255, 4
	s_add_i32 s4, s0, 5
	v_readlane_b32 s0, v250, 8
	v_readlane_b32 s1, v250, 9
	s_cmp_ge_i32 s4, s1
	s_cbranch_scc1 .LBB0_1388
	s_waitcnt vmcnt(0)
	s_waitcnt lgkmcnt(0)
	s_barrier
	s_mov_b64 s[2:3], exec
	v_readlane_b32 s0, v254, 58
	v_readlane_b32 s1, v254, 59
	s_and_b64 s[0:1], s[2:3], s[0:1]
	s_mov_b64 exec, s[0:1]
	s_cbranch_execz .LBB0_1387
	v_mov_b32_e32 v1, v0
	v_readlane_b32 s10, v250, 4
	v_readlane_b32 s11, v250, 5
	v_mov_b32_e32 v20, 0x3400
	s_nop 4
	global_load_dword v20, v20, s[10:11] sc1
	s_nop 0
	v_cmp_ne_u32_e64 s[0:1], 0, v1
	v_cmp_eq_u32_e32 vcc, 0, v1
	s_and_saveexec_b64 s[8:9], vcc
	s_cbranch_execz .LBB0_1369
	v_readlane_b32 s5, v254, 49
	s_waitcnt vmcnt(0) expcnt(0) lgkmcnt(0)
	s_nop 0
	v_mov_b32_e32 v2, s5
	ds_read_b32 v2, v2
	v_readlane_b32 s5, v254, 50
	s_waitcnt lgkmcnt(0)
	v_cmp_ne_u32_e32 vcc, 0, v2
	v_mov_b32_e32 v3, s5
	ds_read_b32 v3, v3
	s_cbranch_vccnz .LBB0_1364
	v_readlane_b32 s12, v250, 0
	v_readlane_b32 s13, v250, 1
	s_load_dwordx2 s[10:11], s[12:13], 0x4
	s_mov_b32 s5, 1
	s_waitcnt lgkmcnt(0)
	s_mul_i32 s12, s10, s33
	s_mul_i32 s12, s12, s11
	s_mov_b64 s[10:11], 0
	s_branch .LBB0_1352

.LBB0_1366:
	s_or_b64 exec, exec, s[14:15]
	s_waitcnt vmcnt(0)
	v_readfirstlane_b32 s5, v5
	v_mul_lo_u32 v2, v3, v2
	s_nop 0
	v_add3_u32 v4, s5, v4, 1
	v_cmp_eq_u32_e32 vcc, v4, v2
	s_and_b64 exec, exec, vcc
	s_cbranch_execz .LBB0_1369
	s_mov_b64 s[10:11], exec
	v_mbcnt_lo_u32_b32 v2, s10, 0
	v_cmp_eq_u32_e32 vcc, 0, v20
	s_cbranch_vccnz .Lxb_cd_nowb
	buffer_wbl2 sc1
.Lxb_cd_nowb:
	s_waitcnt lgkmcnt(0)
	s_waitcnt vmcnt(0)
	v_mbcnt_hi_u32_b32 v2, s11, v2
	v_cmp_eq_u32_e32 vcc, 0, v2
	s_and_b64 s[12:13], exec, vcc
	s_mov_b64 exec, s[12:13]
	s_cbranch_execz .LBB0_1369
	s_bcnt1_i32_b64 s5, s[10:11]
	v_readlane_b32 s10, v252, 49
	v_mov_b32_e32 v2, s5
	v_readlane_b32 s11, v252, 50
	s_nop 4
	global_atomic_add v15, v2, s[10:11]
.LBB0_1369:
	s_or_b64 exec, exec, s[8:9]
	v_readlane_b32 s5, v254, 51
	s_waitcnt lgkmcnt(0)
	v_readlane_b32 s8, v250, 4
	v_add_u32_e32 v14, 0xdc0, v1
	v_mov_b32_e32 v2, s5
	v_readlane_b32 s5, v254, 50
	ds_read_b32 v4, v2
	v_readlane_b32 s9, v250, 5
	v_mov_b32_e32 v2, s5
	ds_read_b32 v2, v2
	s_mov_b32 s5, 1
	s_waitcnt lgkmcnt(0)
	v_lshrrev_b32_e32 v2, v1, v2
	v_and_b32_e32 v2, 1, v2
	v_cmp_eq_u32_e64 s[38:39], 1, v2
	v_lshl_add_u64 v[2:3], v[14:15], 2, s[8:9]
	v_readlane_b32 s12, v252, 49
	s_waitcnt vmcnt(0)
	v_cmp_ne_u32_e32 vcc, 0, v20
	s_nop 1
	v_cmp_eq_u32_e64 s[40:41], s12, v2
	s_and_b64 s[38:39], s[38:39], vcc
	s_andn2_b64 s[40:41], s[40:41], vcc
	s_or_b64 s[38:39], s[38:39], s[40:41]
	s_mov_b64 s[8:9], 0
	s_branch .LBB0_1372
